# attention: one-sided 66-VALU band mask for interior blocks at jj==0/4 (on top of P1/P5 epilogue load batching)
# speedup vs baseline: 1.0035x; 1.0035x over previous
; __device__ __forceinline__ void mask_tile(f32x16& p0, f32x16& p1, int kb0, int lo_, int hi_) {
; #pragma unroll
;     for (int r = 0; r < 16; ++r) { const int kv = kb0 + (r & 3) + 8 * (r >> 2); if (kv < lo_ || kv > hi_) p0[r] = -INFINITY; if (kv + 32 < lo_ || kv + 32 > hi_) p1[r] = -INFINITY; }
; }
; __device__ __forceinline__ void attn_unit(Frame& F, const Ptrs& P, int u, int u_next, bf16x8 (&qa)[4], ScanRider& R) {
;     ...
;         if (jj == 0 || jj == 4 || edge_all) {
;             const int qwA = 128 + r0 + r32, qwB = qwA + 32;
;             const int loA = (qwA - 128) > kmin ? (qwA - 128) : kmin, hiA = (qwA + 128) < kmax ? (qwA + 128) : kmax, loB = (qwB - 128) > kmin ? (qwB - 128) : kmin, hiB = (qwB + 128) < kmax ? (qwB + 128) : kmax;
;             mask_tile(pA0, pA1, 64 * j + 4 * hi, loA, hiA); mask_tile(pB0, pB1, 64 * j + 4 * hi, loB, hiB); }
.LBB0_669:
	s_cmp_gt_i32 s81, 62
	s_cbranch_scc1 .LBB0_662
	s_cmp_eq_u32 s81, 0
	s_cbranch_scc1 .LBB0_662
	v_lshlrev_b32_e32 v237, 2, v14
	v_sub_u32_e32 v237, v177, v237
	s_cmp_eq_u32 s82, 0
	s_cbranch_scc0 .Lattn_mask_hi
	s_nop 7
	v_cmp_lt_i32_e64 s[98:99], 0, v237
	v_cmp_lt_i32_e64 s[100:101], 1, v237
	v_cmp_lt_i32_e64 s[4:5], 2, v237
	v_cndmask_b32_e64 v128, v128, v167, s[98:99]
	v_cndmask_b32_e64 v80, v80, v167, s[98:99]
	v_mov_b32_e32 v96, v167
	v_cmp_lt_i32_e64 s[98:99], 3, v237
	v_cndmask_b32_e64 v129, v129, v167, s[100:101]
	v_cndmask_b32_e64 v81, v81, v167, s[100:101]
	v_mov_b32_e32 v97, v167
	v_cmp_lt_i32_e64 s[100:101], 8, v237
	v_cndmask_b32_e64 v130, v130, v167, s[4:5]
	v_cndmask_b32_e64 v82, v82, v167, s[4:5]
	v_mov_b32_e32 v98, v167
	v_cmp_lt_i32_e64 s[4:5], 9, v237
	v_cndmask_b32_e64 v131, v131, v167, s[98:99]
	v_cndmask_b32_e64 v83, v83, v167, s[98:99]
	v_mov_b32_e32 v99, v167
	v_cmp_lt_i32_e64 s[98:99], 10, v237
	v_cndmask_b32_e64 v132, v132, v167, s[100:101]
	v_cndmask_b32_e64 v84, v84, v167, s[100:101]
	v_mov_b32_e32 v100, v167
	v_cmp_lt_i32_e64 s[100:101], 11, v237
	v_cndmask_b32_e64 v133, v133, v167, s[4:5]
	v_cndmask_b32_e64 v85, v85, v167, s[4:5]
	v_mov_b32_e32 v101, v167
	v_cmp_lt_i32_e64 s[4:5], 16, v237
	v_cndmask_b32_e64 v134, v134, v167, s[98:99]
	v_cndmask_b32_e64 v86, v86, v167, s[98:99]
	v_mov_b32_e32 v102, v167
	v_cmp_lt_i32_e64 s[98:99], 17, v237
	v_cndmask_b32_e64 v135, v135, v167, s[100:101]
	v_cndmask_b32_e64 v87, v87, v167, s[100:101]
	v_mov_b32_e32 v103, v167
	v_cmp_lt_i32_e64 s[100:101], 18, v237
	v_cndmask_b32_e64 v136, v136, v167, s[4:5]
	v_cndmask_b32_e64 v88, v88, v167, s[4:5]
	v_mov_b32_e32 v104, v167
	v_cmp_lt_i32_e64 s[4:5], 19, v237
	v_cndmask_b32_e64 v137, v137, v167, s[98:99]
	v_cndmask_b32_e64 v89, v89, v167, s[98:99]
	v_mov_b32_e32 v105, v167
	v_cmp_lt_i32_e64 s[98:99], 24, v237
	v_cndmask_b32_e64 v138, v138, v167, s[100:101]
	v_cndmask_b32_e64 v90, v90, v167, s[100:101]
	v_mov_b32_e32 v106, v167
	v_cmp_lt_i32_e64 s[100:101], 25, v237
	v_cndmask_b32_e64 v139, v139, v167, s[4:5]
	v_cndmask_b32_e64 v91, v91, v167, s[4:5]
	v_mov_b32_e32 v107, v167
	v_cmp_lt_i32_e64 s[4:5], 26, v237
	v_cndmask_b32_e64 v140, v140, v167, s[98:99]
	v_cndmask_b32_e64 v92, v92, v167, s[98:99]
	v_mov_b32_e32 v108, v167
	v_cmp_lt_i32_e64 s[98:99], 27, v237
	v_cndmask_b32_e64 v141, v141, v167, s[100:101]
	v_cndmask_b32_e64 v93, v93, v167, s[100:101]
	v_mov_b32_e32 v109, v167
	v_cndmask_b32_e64 v142, v142, v167, s[4:5]
	v_cndmask_b32_e64 v94, v94, v167, s[4:5]
	v_mov_b32_e32 v110, v167
	v_cndmask_b32_e64 v143, v143, v167, s[98:99]
	v_cndmask_b32_e64 v95, v95, v167, s[98:99]
	v_mov_b32_e32 v111, v167
	s_branch .LBB0_663
.Lattn_mask_hi:
	s_nop 7
	v_cmp_gt_i32_e64 s[98:99], 0, v237
	v_cmp_gt_i32_e64 s[100:101], 1, v237
	v_cmp_gt_i32_e64 s[4:5], 2, v237
	v_cndmask_b32_e64 v128, v128, v167, s[98:99]
	v_cndmask_b32_e64 v80, v80, v167, s[98:99]
	v_mov_b32_e32 v112, v167
	v_cmp_gt_i32_e64 s[98:99], 3, v237
	v_cndmask_b32_e64 v129, v129, v167, s[100:101]
	v_cndmask_b32_e64 v81, v81, v167, s[100:101]
	v_mov_b32_e32 v113, v167
	v_cmp_gt_i32_e64 s[100:101], 8, v237
	v_cndmask_b32_e64 v130, v130, v167, s[4:5]
	v_cndmask_b32_e64 v82, v82, v167, s[4:5]
	v_mov_b32_e32 v114, v167
	v_cmp_gt_i32_e64 s[4:5], 9, v237
	v_cndmask_b32_e64 v131, v131, v167, s[98:99]
	v_cndmask_b32_e64 v83, v83, v167, s[98:99]
	v_mov_b32_e32 v115, v167
	v_cmp_gt_i32_e64 s[98:99], 10, v237
	v_cndmask_b32_e64 v132, v132, v167, s[100:101]
	v_cndmask_b32_e64 v84, v84, v167, s[100:101]
	v_mov_b32_e32 v116, v167
	v_cmp_gt_i32_e64 s[100:101], 11, v237
	v_cndmask_b32_e64 v133, v133, v167, s[4:5]
	v_cndmask_b32_e64 v85, v85, v167, s[4:5]
	v_mov_b32_e32 v117, v167
	v_cmp_gt_i32_e64 s[4:5], 16, v237
	v_cndmask_b32_e64 v134, v134, v167, s[98:99]
	v_cndmask_b32_e64 v86, v86, v167, s[98:99]
	v_mov_b32_e32 v118, v167
	v_cmp_gt_i32_e64 s[98:99], 17, v237
	v_cndmask_b32_e64 v135, v135, v167, s[100:101]
	v_cndmask_b32_e64 v87, v87, v167, s[100:101]
	v_mov_b32_e32 v119, v167
	v_cmp_gt_i32_e64 s[100:101], 18, v237
	v_cndmask_b32_e64 v136, v136, v167, s[4:5]
	v_cndmask_b32_e64 v88, v88, v167, s[4:5]
	v_mov_b32_e32 v120, v167
	v_cmp_gt_i32_e64 s[4:5], 19, v237
	v_cndmask_b32_e64 v137, v137, v167, s[98:99]
	v_cndmask_b32_e64 v89, v89, v167, s[98:99]
	v_mov_b32_e32 v121, v167
	v_cmp_gt_i32_e64 s[98:99], 24, v237
	v_cndmask_b32_e64 v138, v138, v167, s[100:101]
	v_cndmask_b32_e64 v90, v90, v167, s[100:101]
	v_mov_b32_e32 v122, v167
	v_cmp_gt_i32_e64 s[100:101], 25, v237
	v_cndmask_b32_e64 v139, v139, v167, s[4:5]
	v_cndmask_b32_e64 v91, v91, v167, s[4:5]
	v_mov_b32_e32 v123, v167
	v_cmp_gt_i32_e64 s[4:5], 26, v237
	v_cndmask_b32_e64 v140, v140, v167, s[98:99]
	v_cndmask_b32_e64 v92, v92, v167, s[98:99]
	v_mov_b32_e32 v124, v167
	v_cmp_gt_i32_e64 s[98:99], 27, v237
	v_cndmask_b32_e64 v141, v141, v167, s[100:101]
	v_cndmask_b32_e64 v93, v93, v167, s[100:101]
	v_mov_b32_e32 v125, v167
	v_cndmask_b32_e64 v142, v142, v167, s[4:5]
	v_cndmask_b32_e64 v94, v94, v167, s[4:5]
	v_mov_b32_e32 v126, v167
	v_cndmask_b32_e64 v143, v143, v167, s[98:99]
	v_cndmask_b32_e64 v95, v95, v167, s[98:99]
	v_mov_b32_e32 v127, v167
	s_branch .LBB0_663

; __global__ void __launch_bounds__(NWAVES * 64, 2) mk_fwd(Args args) {
	.amdhsa_kernel _Z6mk_fwd4Args
		.amdhsa_group_segment_fixed_size 0
		.amdhsa_private_segment_fixed_size 0
		.amdhsa_kernarg_size 440
		.amdhsa_user_sgpr_count 2
		.amdhsa_user_sgpr_dispatch_ptr 0
		.amdhsa_user_sgpr_queue_ptr 0
		.amdhsa_user_sgpr_kernarg_segment_ptr 1
		.amdhsa_user_sgpr_dispatch_id 0
		.amdhsa_user_sgpr_kernarg_preload_length 0
		.amdhsa_user_sgpr_kernarg_preload_offset 0
		.amdhsa_user_sgpr_private_segment_size 0
		.amdhsa_uses_dynamic_stack 0
		.amdhsa_enable_private_segment 0
		.amdhsa_system_sgpr_workgroup_id_x 1
		.amdhsa_system_sgpr_workgroup_id_y 0
		.amdhsa_system_sgpr_workgroup_id_z 0
		.amdhsa_system_sgpr_workgroup_info 0
		.amdhsa_system_vgpr_workitem_id 0
		.amdhsa_next_free_vgpr 253
		.amdhsa_next_free_sgpr 102
		.amdhsa_accum_offset 256
		.amdhsa_reserve_vcc 1
		.amdhsa_float_round_mode_32 0
		.amdhsa_float_round_mode_16_64 0
		.amdhsa_float_denorm_mode_32 3
		.amdhsa_float_denorm_mode_16_64 3
		.amdhsa_dx10_clamp 1
		.amdhsa_ieee_mode 1
		.amdhsa_fp16_overflow 0
		.amdhsa_tg_split 0
		.amdhsa_exception_fp_ieee_invalid_op 0
		.amdhsa_exception_fp_denorm_src 0
		.amdhsa_exception_fp_ieee_div_zero 0
		.amdhsa_exception_fp_ieee_overflow 0
		.amdhsa_exception_fp_ieee_underflow 0
		.amdhsa_exception_fp_ieee_inexact 0
		.amdhsa_exception_int_div_zero 0
	.end_amdhsa_kernel

; __global__ void __launch_bounds__(NWAVES * 64, 2) mk_fwd(Args args) {
.Lfunc_end0:
	.size	_Z6mk_fwd4Args, .Lfunc_end0-_Z6mk_fwd4Args
	.set _Z6mk_fwd4Args.num_vgpr, 253
	.set _Z6mk_fwd4Args.num_agpr, 0
	.set _Z6mk_fwd4Args.numbered_sgpr, 102
	.set _Z6mk_fwd4Args.num_named_barrier, 0
	.set _Z6mk_fwd4Args.private_seg_size, 0
	.set _Z6mk_fwd4Args.uses_vcc, 1
	.set _Z6mk_fwd4Args.uses_flat_scratch, 0
	.set _Z6mk_fwd4Args.has_dyn_sized_stack, 0
	.set _Z6mk_fwd4Args.has_recursion, 0
	.set _Z6mk_fwd4Args.has_indirect_call, 0

; __global__ void __launch_bounds__(NWAVES * 64, 2) mk_fwd(Args args) {
amdhsa.kernels:
  - .agpr_count:     0
    .args:
      - .offset:         0
        .size:           184
        .value_kind:     by_value
      - .offset:         184
        .size:           4
        .value_kind:     hidden_block_count_x
      - .offset:         188
        .size:           4
        .value_kind:     hidden_block_count_y
      - .offset:         192
        .size:           4
        .value_kind:     hidden_block_count_z
      - .offset:         196
        .size:           2
        .value_kind:     hidden_group_size_x
      - .offset:         198
        .size:           2
        .value_kind:     hidden_group_size_y
      - .offset:         200
        .size:           2
        .value_kind:     hidden_group_size_z
      - .offset:         202
        .size:           2
        .value_kind:     hidden_remainder_x
      - .offset:         204
        .size:           2
        .value_kind:     hidden_remainder_y
      - .offset:         206
        .size:           2
        .value_kind:     hidden_remainder_z
      - .offset:         224
        .size:           8
        .value_kind:     hidden_global_offset_x
      - .offset:         232
        .size:           8
        .value_kind:     hidden_global_offset_y
      - .offset:         240
        .size:           8
        .value_kind:     hidden_global_offset_z
      - .offset:         248
        .size:           2
        .value_kind:     hidden_grid_dims
      - .offset:         304
        .size:           4
        .value_kind:     hidden_dynamic_lds_size
    .group_segment_fixed_size: 0
    .kernarg_segment_align: 8
    .kernarg_segment_size: 440
    .language:       OpenCL C
    .language_version:
      - 2
      - 0
    .max_flat_workgroup_size: 512
    .name:           _Z6mk_fwd4Args
    .private_segment_fixed_size: 0
    .sgpr_count:     108
    .sgpr_spill_count: 51
    .symbol:         _Z6mk_fwd4Args.kd
    .uniform_work_group_size: 1
    .uses_dynamic_stack: false
    .vgpr_count:     253
    .vgpr_spill_count: 0
    .wavefront_size: 64
